# XCC census taken off the critical path (counter snapshot loaded during the weight-conversion loop, reduced by wave 0 before the row pass); first seam now the hand-written body too
# speedup vs baseline: 1.0065x; 1.0022x over previous
; #define LAS __attribute__((address_space(3)))
; __device__ __forceinline__ void p0_convert(const Args& a, LAS float* scr, int gw, int NGW, int lane) {
;     constexpr int I_IN = 104 * 16, I_PA = 16 * 8, I_PB = 16 * 16, I_OUT = 16 * 16, I_GU = 88 * 16, I_DN = 16 * 44, TOTAL = I_IN + I_PA + I_PB + I_OUT + I_GU + I_DN;
;     for (int it = gw; it < TOTAL; it += NGW) {
;         int r = it, kind, K; size_t dsto;
;         if (r < I_IN) { kind = 0; K = 1024; dsto = WS_WIN; }
;         else if ((r -= I_IN) < I_PA) { kind = 1; K = 512; dsto = WS_WPA; }
;         else if ((r -= I_PA) < I_PB) { kind = 2; K = 1024; dsto = WS_WPB; }
;         else if ((r -= I_PB) < I_OUT) { kind = 3; K = 1024; dsto = WS_WOUT; }
;         else if ((r -= I_OUT) < I_GU) { kind = 4; K = 1024; dsto = WS_WGU; }
;         else { r -= I_GU; kind = 5; K = 2816; dsto = WS_WDN; }
;         const int ktiles = K >> 6, n0 = (r / ktiles) * 64, k0 = (r % ktiles) * 64, n = n0 + lane;
.LBB0_88:
	s_or_b64 exec, exec, s[6:7]
	s_cmpk_gt_i32 s81, 0x113f
	s_cbranch_scc1 .LBB0_129
	v_and_b32_e32 v0, 31, v178
	s_mul_i32 s0, s93, 0x4100
	v_lshlrev_b32_e32 v5, 3, v0
	v_lshlrev_b32_e32 v0, 2, v0
	v_mov_b32_e32 v1, 0
	s_movk_i32 s6, 0x104
	v_lshrrev_b32_e32 v20, 5, v176
	v_lshl_add_u64 v[2:3], s[54:55], 0, v[0:1]
	v_mov_b32_e32 v0, s0
	s_add_i32 s3, s0, 0
	v_mul_u32_u24_e32 v4, 0x104, v176
	v_mad_u32_u24 v0, v20, s6, v0
	s_mov_b32 s1, 0
	v_or_b32_e32 v21, 14, v20
	v_add3_u32 v22, v0, v5, 0
	v_or_b32_e32 v23, 12, v20
	v_or_b32_e32 v24, 10, v20
	v_or_b32_e32 v25, 8, v20
	v_or_b32_e32 v26, 6, v20
	v_or_b32_e32 v27, 4, v20
	v_or_b32_e32 v28, 2, v20
	s_movk_i32 s72, 0x1200
	v_add_u32_e32 v29, s3, v4
	s_xor_b32 s73, s81, 0x400
	s_add_u32 s98, s54, 0x22a2400
	s_addc_u32 s99, s55, 0
	v_lshlrev_b32_e32 v254, 8, v176
	v_and_b32_e32 v254, 0xf00, v254
.LBB0_90:
	global_load_dword v253, v254, s[98:99] sc1
	s_cmpk_gt_i32 s73, 0x67f
	s_cselect_b64 s[8:9], -1, 0
	s_cmpk_lt_i32 s73, 0x680
	s_cbranch_scc1 .LBB0_104
	s_cmpk_gt_u32 s73, 0x6ff
	s_mov_b64 s[30:31], -1
	s_cbranch_scc0 .LBB0_102
	s_cmpk_gt_u32 s73, 0x7ff
	s_mov_b64 s[34:35], -1
	s_cbranch_scc0 .LBB0_100
	s_cmpk_gt_u32 s73, 0x8ff
	s_mov_b64 s[28:29], -1
	s_cbranch_scc0 .LBB0_98
	s_cmpk_gt_u32 s73, 0xe7f
	s_mov_b64 s[6:7], -1
	s_cbranch_scc0 .LBB0_96
	s_add_i32 s74, s73, 0xfffff180
	s_mov_b64 s[6:7], 0

; __device__ __forceinline__ unsigned xb_ld(unsigned* p)              { return __hip_atomic_load(p, __ATOMIC_RELAXED, __HIP_MEMORY_SCOPE_AGENT); }
; __device__ __forceinline__ void xcd_barrier_complete(unsigned* bar, unsigned x, unsigned& nloc, unsigned& nx) {
;     const unsigned G = gridDim.x * gridDim.y * gridDim.z;
;     unsigned sum, cnt, mine, sp = 0u;
;     for (;;) {
;         sum = 0u; cnt = 0u; mine = 0u;
; #pragma unroll
;         for (unsigned j = 0; j < 16; ++j) { const unsigned c = xb_ld(&bar[XB_XCNT(j)]); sum += c; cnt += (c > 0u) ? 1u : 0u; mine = (j == x) ? c : mine; }
;         if (sum == G) break;
;         __builtin_amdgcn_s_sleep(1);
;         if ((++sp & 255u) == 0u) { if (xb_ld(&bar[XB_TMO])) break; if (sp > XB_SPIN_CAP) { atomicAdd(&bar[XB_TMO], 1u); break; } }
;     }
;     nloc = mine > 0u ? mine : 1u; nx = cnt > 0u ? cnt : 1u;
; }
.LBB0_129:
	s_cmp_lg_u32 s93, 0
	s_cbranch_scc1 .Lcz_done
	s_getreg_b32 s3, hwreg(HW_REG_XCC_ID, 0, 4)
	s_and_b32 s3, s3, 15
	s_add_u32 s98, s54, 0x22a2400
	s_addc_u32 s99, s55, 0
	v_lshlrev_b32_e32 v254, 8, v176
	v_and_b32_e32 v254, 0xf00, v254
.Lcz_reduce:
	v_readlane_b32 s0, v253, 0
	v_readlane_b32 s1, v253, 1
	s_add_i32 s0, s0, s1
	v_readlane_b32 s1, v253, 2
	s_add_i32 s0, s0, s1
	v_readlane_b32 s1, v253, 3
	s_add_i32 s0, s0, s1
	v_readlane_b32 s1, v253, 4
	s_add_i32 s0, s0, s1
	v_readlane_b32 s1, v253, 5
	s_add_i32 s0, s0, s1
	v_readlane_b32 s1, v253, 6
	s_add_i32 s0, s0, s1
	v_readlane_b32 s1, v253, 7
	s_add_i32 s0, s0, s1
	v_readlane_b32 s1, v253, 8
	s_add_i32 s0, s0, s1
	v_readlane_b32 s1, v253, 9
	s_add_i32 s0, s0, s1
	v_readlane_b32 s1, v253, 10
	s_add_i32 s0, s0, s1
	v_readlane_b32 s1, v253, 11
	s_add_i32 s0, s0, s1
	v_readlane_b32 s1, v253, 12
	s_add_i32 s0, s0, s1
	v_readlane_b32 s1, v253, 13
	s_add_i32 s0, s0, s1
	v_readlane_b32 s1, v253, 14
	s_add_i32 s0, s0, s1
	v_readlane_b32 s1, v253, 15
	s_add_i32 s0, s0, s1
	s_cmp_eq_u32 s0, s58
	s_cbranch_scc1 .Lcz_ok
	s_sleep 1
	global_load_dword v253, v254, s[98:99] sc1
	s_waitcnt vmcnt(0)
	s_branch .Lcz_reduce
.Lcz_ok:
	v_cmp_ne_u32_e32 vcc, 0, v253
	v_readlane_b32 s6, v253, s3
	s_and_b32 s1, vcc_lo, 0xffff
	s_bcnt1_i32_b32 s1, s1
	v_mov_b32_e32 v255, 0x23ff0
	v_mov_b32_e32 v254, s6
	v_mov_b32_e32 v253, s1
	ds_write2_b32 v255, v254, v253 offset1:1
	s_waitcnt lgkmcnt(0)

; __device__ __forceinline__ unsigned xb_add(unsigned* p, unsigned v) { return __hip_atomic_fetch_add(p, v, __ATOMIC_RELAXED, __HIP_MEMORY_SCOPE_AGENT); }
; __device__ __forceinline__ void xcd_barrier(const XcdBarrier& b) {
;     asm volatile("s_waitcnt vmcnt(0)" ::: "memory");
;     __syncthreads();
;     if (threadIdx.x == 0) {
;         unsigned* bar = b.bar;
;         __builtin_amdgcn_s_waitcnt(0);
;         unsigned nloc = b.st[0], nx = b.st[1];
;         if (nloc == 0u) { xcd_barrier_complete(bar, b.x, nloc, nx); b.st[0] = nloc; b.st[1] = nx; }
;         const unsigned old = xb_add(&bar[XB_XSUB(b.x)], 1u);
;         const unsigned gen = old / nloc;
;         if (old + 1u == (gen + 1u) * nloc) {
;             __builtin_amdgcn_fence(__ATOMIC_RELEASE, "agent");
;             asm volatile("s_waitcnt vmcnt(0)" ::: "memory");
;             const unsigned og = xb_add(&bar[XB_TOP], 1u);
;             const unsigned tg = og / nx;
;             if (og + 1u == (tg + 1u) * nx) xb_add(&bar[XB_TOPGEN], 1u);
.LBB0_144:
	s_cmp_lt_i32 s56, 2
	s_cselect_b64 s[10:11], -1, 0
	s_cmp_gt_i32 s57, 1
	s_cselect_b64 s[0:1], -1, 0
	s_and_b64 s[0:1], s[10:11], s[0:1]
	s_andn2_b64 vcc, exec, s[0:1]
	s_cbranch_vccnz .LBB0_443
	s_andn2_b64 vcc, exec, s[4:5]
	s_cbranch_vccnz .LBB0_199
	s_getreg_b32 s3, hwreg(HW_REG_XCC_ID, 0, 4)
	s_waitcnt vmcnt(0)
	v_cmp_eq_u32_e32 vcc, 0, v178
	s_waitcnt lgkmcnt(0)
	s_barrier
	s_and_saveexec_b64 s[0:1], vcc
	s_cbranch_execz .LBB0_198
	buffer_inv sc1
	v_mov_b32_e32 v0, 0x23ff0
	ds_read2_b32 v[0:1], v0 offset1:1
	s_and_b32 s98, s3, 15
	s_lshl_b32 s98, s98, 8
	s_add_u32 s98, s54, s98
	s_addc_u32 s99, s55, 0
	s_add_u32 s98, s98, 0x22a3400
	s_addc_u32 s99, s99, 0
	v_mov_b32_e32 v2, 0
	v_mov_b32_e32 v3, 1
	global_atomic_add v4, v2, v3, s[98:99] sc0
	s_add_u32 s100, s54, 0x22a5400
	s_addc_u32 s101, s55, 0
	s_waitcnt vmcnt(0) lgkmcnt(0)
	v_mul_u32_u24_e32 v0, 1, v0
	v_mul_u32_u24_e32 v1, 1, v1
	v_add_u32_e32 v4, 1, v4
	v_cmp_eq_u32_e32 vcc, v4, v0
	s_cbranch_vccz .Lxb_poll_s0
	buffer_wbl2 sc1
	s_waitcnt vmcnt(0)
	global_atomic_add v2, v3, s[100:101]

;     __host__ __device__ bool next(int i, Unit& u) const {
;         const long L = (long)i * G + c; if (L >= nwg) return false;
;         int wgid = (int)L; { const int q = nwg / NXCD, r = nwg % NXCD, xcd = wgid % NXCD, off = wgid / NXCD; wgid = (xcd < r ? xcd * (q + 1) : r * (q + 1) + (xcd - r) * q) + off; }
;         const int nig = WGM * nN, gid = wgid / nig, fm = gid * WGM, gsz = (nM - fm) < WGM ? (nM - fm) : WGM;
;         u.pm = fm + ((wgid % nig) % gsz); u.pn = (wgid % nig) / gsz; return true;
.Lxb_done_s0:
.LBB0_198:
	s_or_b64 exec, exec, s[0:1]
	s_waitcnt lgkmcnt(0)
	s_barrier
.LBB0_199:
	s_cmpk_lt_i32 s2, 0x6e8
	s_cselect_b64 s[0:1], -1, 0
	s_cmpk_gt_i32 s2, 0x6e7
	v_readfirstlane_b32 s3, v178
	s_cbranch_scc1 .LBB0_201
	s_ashr_i32 s4, s2, 31
	s_lshr_b32 s4, s4, 29
	s_add_i32 s4, s2, s4
	s_ashr_i32 s5, s4, 3
	s_and_b32 s4, s4, -8
	s_sub_i32 s4, s2, s4
	s_cmp_lt_i32 s4, 0
	s_movk_i32 s6, 0xde
	s_cselect_b32 s6, s6, 0xdd
	s_mul_i32 s4, s4, s6
	s_add_i32 s4, s4, s5
	s_mul_hi_i32 s5, s4, 0x4ec4ec4f
	s_lshr_b32 s6, s5, 31
	s_ashr_i32 s5, s5, 6
	s_add_i32 s5, s5, s6
	s_lshl_b32 s7, s5, 3
	s_sub_i32 s6, 0x44, s7
	s_mulk_i32 s5, 0xd0
	s_min_u32 s8, s6, 8
	s_sub_i32 s9, s4, s5
	s_sext_i32_i16 s4, s9
	v_cvt_f32_ubyte0_e32 v1, s8
	v_cvt_f32_i32_e32 v0, s4
	v_rcp_iflag_f32_e32 v2, v1
	s_ashr_i32 s4, s4, 30
	s_or_b32 s6, s4, 1
	v_mul_f32_e32 v2, v0, v2
	v_trunc_f32_e32 v2, v2
	v_fma_f32 v0, -v2, v1, v0
	v_cvt_i32_f32_e32 v2, v2
	v_cmp_ge_f32_e64 s[4:5], |v0|, v1
	s_and_b64 s[4:5], s[4:5], exec
	s_cselect_b32 s4, s6, 0
	v_readfirstlane_b32 s5, v2
	s_add_i32 s4, s5, s4
	s_sext_i32_i16 s6, s4
	s_mul_i32 s4, s4, s8
	s_sub_i32 s4, s9, s4
	s_sext_i32_i16 s4, s4
	s_add_i32 s4, s7, s4
